# row-pass output stores write-through (sc1) so the barrier-time L2 write-back has little left to flush
# baseline (speedup 1.0000x reference)
; __device__ __forceinline__ void xcd_barrier(const XcdBarrier& b) {
;     asm volatile("s_waitcnt vmcnt(0)" ::: "memory");
;     __syncthreads();
;     if (threadIdx.x == 0) {
;         unsigned* bar = b.bar;
;         __builtin_amdgcn_s_waitcnt(0);
; template <bool HAS_F, bool HAS_H, bool XIN_B = false, bool XOUT_B = false> ...
;     ...
;     for (int row = row_lo; row < row_lo + RPW; ++row) {
;         f32x4 x[4]; u32x2 fwv[4];
; #pragma unroll
;         for (int j = 0; j < 4; ++j) { x[j] = xn[j]; if (HAS_F) fwv[j] = fn[j]; }
;         { const int rn = (row + 1 < row_lo + RPW) ? row + 1 : row;
; #pragma unroll
;           for (int j = 0; j < 4; ++j) { RP_LDX(xn[j], rn, j); if (HAS_F) fn[j] = __builtin_nontemporal_load((const GAS u32x2*)(Fb + (size_t)rn * DM + 256 * j + 4 * lane)); } }
;         if (HAS_F) {
;             f32x4 f[4]; float ss = 0.f;
; #pragma unroll
;             for (int j = 0; j < 4; ++j) { const u32x2 fw = fwv[j];
;                 f[j] = (f32x4){__uint_as_float(fw.x << 16), __uint_as_float(fw.x & 0xffff0000u), __uint_as_float(fw.y << 16), __uint_as_float(fw.y & 0xffff0000u)}; ss += (f[j].x * f[j].x + f[j].y * f[j].y) + (f[j].z * f[j].z + f[j].w * f[j].w); }
;             const float rstd = 1.0f / sqrtf(wave_sum(ss) * (1.0f / DM) + RMS_EPS);
; #pragma unroll
;             for (int j = 0; j < 4; ++j) { x[j] = x[j] + f[j] * rstd * Cg[j];
;                 if (XOUT_B) { u32x2 w; w.x = pk_bf16(x[j].x, x[j].y); w.y = pk_bf16(x[j].z, x[j].w); *(GAS u32x2*)(xoutb + (size_t)row * DM + 256 * j + 4 * lane) = w;
;                     x[j] = (f32x4){__uint_as_float(w.x << 16), __uint_as_float(w.x & 0xffff0000u), __uint_as_float(w.y << 16), __uint_as_float(w.y & 0xffff0000u)}; }
;                 else __builtin_nontemporal_store(x[j], (GAS f32x4*)(xout + (size_t)row * DM + 256 * j + 4 * lane)); }
;         }
;         if (HAS_H) {
;             float ss = 0.f;
; #pragma unroll
;             for (int j = 0; j < 4; ++j) ss += (x[j].x * x[j].x + x[j].y * x[j].y) + (x[j].z * x[j].z + x[j].w * x[j].w);
;             const float rstd = 1.0f / sqrtf(wave_sum(ss) * (1.0f / DM) + RMS_EPS);
; #pragma unroll
;             for (int j = 0; j < 4; ++j) { const f32x4 h = x[j] * rstd * A[j] + Sh[j]; u32x2 w; w.x = pk_bf16(h.x, h.y); w.y = pk_bf16(h.z, h.w);
;                 *(GAS u32x2*)(H + (size_t)row * DM + 256 * j + 4 * lane) = w; }
.LBB0_91:
	s_add_i32 s7, s11, 1
	v_mul_f32_e32 v58, v17, v17
	v_mul_f32_e32 v59, v19, v19
	v_mul_f32_e32 v60, v21, v21
	v_mul_f32_e32 v61, v23, v23
	v_mul_f32_e32 v57, v57, v57
	v_mul_f32_e32 v56, v56, v56
	v_mul_f32_e32 v62, v29, v29
	v_mul_f32_e32 v63, v31, v31
	v_fmac_f32_e32 v58, v16, v16
	v_fmac_f32_e32 v59, v18, v18
	v_fmac_f32_e32 v60, v20, v20
	v_fmac_f32_e32 v61, v22, v22
	s_cmp_lt_i32 s11, s70
	v_fmac_f32_e32 v57, v54, v54
	v_fmac_f32_e32 v56, v55, v55
	v_fmac_f32_e32 v62, v28, v28
	v_fmac_f32_e32 v63, v30, v30
	v_add_f32_e32 v54, v58, v59
	v_add_f32_e32 v55, v60, v61
	s_cselect_b64 s[4:5], -1, 0
	v_add_f32_e32 v58, v62, v63
	s_and_b64 s[4:5], s[4:5], exec
	v_add_f32_e32 v54, v54, v55
	v_add_f32_e32 v56, v57, v56
	s_cselect_b32 s6, s7, s11
	v_add_f32_e32 v54, v58, v54
	s_mov_b32 s11, s7
	s_ashr_i32 s7, s6, 31
	v_add_f32_e32 v54, v56, v54
	s_lshl_b64 s[6:7], s[6:7], 12
	v_lshl_add_u64 v[70:71], v[32:33], 0, s[6:7]
	v_add_f32_dpp v54, v54, v54 quad_perm:[1,0,3,2] row_mask:0xf bank_mask:0xf bound_ctrl:1
	s_nop 1
	v_add_f32_dpp v58, v54, v54 quad_perm:[2,3,0,1] row_mask:0xf bank_mask:0xf bound_ctrl:1
	s_mov_b64 exec, s[4:5]
	global_load_dwordx4 v[54:57], v[70:71], off nt
	s_mov_b64 exec, -1
	s_nop 4
	s_nop 0
	v_add_f32_dpp v72, v58, v58 row_half_mirror row_mask:0xf bank_mask:0xf bound_ctrl:1
	s_mov_b64 exec, s[4:5]
	global_load_dwordx4 v[58:61], v[70:71], off offset:1024 nt
	global_load_dwordx4 v[62:65], v[70:71], off offset:2048 nt
	global_load_dwordx4 v[66:69], v[70:71], off offset:3072 nt
	s_mov_b64 exec, -1
	s_nop 4
	v_add_f32_dpp v70, v72, v72 row_mirror row_mask:0xf bank_mask:0xf bound_ctrl:1
	v_mov_b32_e32 v71, v70
	s_nop 1
	v_permlane16_swap_b32_e32 v70, v71
	v_add_f32_e32 v70, v70, v71
	v_mov_b32_e32 v71, v70
	s_nop 1
	v_permlane32_swap_b32_e32 v70, v71
	v_add_f32_e32 v70, v70, v71
	v_fmamk_f32 v70, v70, 0x3a800000, v52
	v_mul_f32_e32 v71, 0x4f800000, v70
	v_cmp_gt_f32_e32 vcc, s10, v70
	s_nop 1
	v_cndmask_b32_e32 v70, v70, v71, vcc
	v_sqrt_f32_e32 v71, v70
	s_nop 0
	v_add_u32_e32 v72, -1, v71
	v_add_u32_e32 v73, 1, v71
	v_fma_f32 v74, -v72, v71, v70
	v_fma_f32 v75, -v73, v71, v70
	v_cmp_ge_f32_e64 s[6:7], 0, v74
	s_nop 1
	v_cndmask_b32_e64 v71, v71, v72, s[6:7]
	v_cmp_lt_f32_e64 s[6:7], 0, v75
	s_nop 1
	v_cndmask_b32_e64 v71, v71, v73, s[6:7]
	v_mul_f32_e32 v72, 0x37800000, v71
	v_cndmask_b32_e32 v71, v71, v72, vcc
	v_cmp_class_f32_e32 vcc, v70, v53
	s_nop 1
	v_cndmask_b32_e32 v70, v71, v70, vcc
	v_div_scale_f32 v71, s[6:7], v70, v70, 1.0
	v_rcp_f32_e32 v73, v71
	v_div_scale_f32 v72, vcc, 1.0, v70, 1.0
	v_fma_f32 v74, -v71, v73, 1.0
	v_fmac_f32_e32 v73, v74, v73
	v_mul_f32_e32 v74, v72, v73
	v_fma_f32 v75, -v71, v74, v72
	v_fmac_f32_e32 v74, v75, v73
	v_fma_f32 v71, -v71, v74, v72
	v_div_fmas_f32 v71, v71, v73, v74
	v_div_fixup_f32 v70, v71, v70, 1.0
	v_pk_mul_f32 v[16:17], v[16:17], v[70:71] op_sel_hi:[1,0]
	v_pk_mul_f32 v[18:19], v[18:19], v[70:71] op_sel_hi:[1,0]
	v_pk_fma_f32 v[16:17], v[38:39], v[16:17], v[8:9]
	v_pk_mul_f32 v[20:21], v[20:21], v[70:71] op_sel_hi:[1,0]
	v_pk_mul_f32 v[22:23], v[22:23], v[70:71] op_sel_hi:[1,0]
	v_pk_fma_f32 v[18:19], v[36:37], v[18:19], v[10:11]
	v_cvt_pk_bf16_f32 v16, v16, v17
	v_pk_mul_f32 v[28:29], v[28:29], v[70:71] op_sel_hi:[1,0]
	v_cvt_pk_bf16_f32 v17, v18, v19
	v_pk_mul_f32 v[30:31], v[30:31], v[70:71] op_sel_hi:[1,0]
	v_pk_mul_f32 v[24:25], v[24:25], v[70:71] op_sel_hi:[1,0]
	v_pk_mul_f32 v[26:27], v[26:27], v[70:71] op_sel_hi:[1,0]
	v_pk_fma_f32 v[22:23], v[40:41], v[22:23], v[2:3]
	v_pk_fma_f32 v[20:21], v[42:43], v[20:21], v[0:1]
	global_store_dwordx2 v[34:35], v[16:17], off offset:-1536 sc1
	v_cvt_pk_bf16_f32 v16, v20, v21
	v_cvt_pk_bf16_f32 v17, v22, v23
	v_pk_fma_f32 v[30:31], v[44:45], v[30:31], v[6:7]
	v_pk_fma_f32 v[28:29], v[46:47], v[28:29], v[4:5]
	v_pk_fma_f32 v[26:27], v[48:49], v[26:27], v[14:15]
	v_pk_fma_f32 v[24:25], v[50:51], v[24:25], v[12:13]
	global_store_dwordx2 v[34:35], v[16:17], off offset:-1024 sc1
	v_cvt_pk_bf16_f32 v16, v28, v29
	v_cvt_pk_bf16_f32 v17, v30, v31
	global_store_dwordx2 v[34:35], v[16:17], off offset:-512 sc1
	v_cvt_pk_bf16_f32 v16, v24, v25
	v_cvt_pk_bf16_f32 v17, v26, v27
	global_store_dwordx2 v[34:35], v[16:17], off sc1
	s_waitcnt vmcnt(4)
	v_mov_b64_e32 v[24:25], v[66:67]
	v_lshl_add_u64 v[34:35], v[34:35], 0, s[8:9]
	v_mov_b32_e32 v16, v54
	v_mov_b32_e32 v17, v55
	v_mov_b32_e32 v18, v56
	v_mov_b32_e32 v19, v57
	v_mov_b32_e32 v20, v58
	v_mov_b32_e32 v21, v59
	v_mov_b32_e32 v22, v60
	v_mov_b32_e32 v23, v61
	v_mov_b32_e32 v28, v62
	v_mov_b32_e32 v29, v63
	v_mov_b32_e32 v30, v64
	v_mov_b32_e32 v31, v65
	v_mov_b32_e32 v54, v66
	v_mov_b32_e32 v57, v67
	v_mov_b32_e32 v55, v68
	v_mov_b32_e32 v56, v69
	v_mov_b64_e32 v[26:27], v[68:69]
	s_mov_b64 vcc, s[4:5]
	s_cbranch_vccnz .LBB0_91
	s_waitcnt vmcnt(0)
	s_barrier
	s_and_saveexec_b64 s[4:5], s[26:27]
	s_xor_b64 s[38:39], exec, s[4:5]
	s_cbranch_execz .LBB0_137
	s_add_i32 s4, 0, 0x20020
	v_mov_b32_e32 v0, s4
	s_waitcnt vmcnt(0) expcnt(0) lgkmcnt(0)
	ds_read_b32 v2, v0
	s_add_i32 s4, 0, 0x20024
	v_mov_b32_e32 v0, s4
	ds_read_b32 v0, v0
	s_waitcnt lgkmcnt(1)
	v_cmp_ne_u32_e32 vcc, 0, v2
	s_cbranch_vccnz .LBB0_107
	s_add_u32 s4, s40, 0x80200
	s_addc_u32 s5, s41, 0
	s_add_u32 s8, s40, 0x80400
	s_addc_u32 s9, s41, 0
	s_add_u32 s10, s40, 0x80500
	s_addc_u32 s11, s41, 0
	s_add_u32 s12, s40, 0x80600
	s_addc_u32 s13, s41, 0
	s_add_u32 s14, s40, 0x80700
	s_addc_u32 s15, s41, 0
	s_add_u32 s16, s40, 0x80800
	s_addc_u32 s17, s41, 0
	s_add_u32 s18, s40, 0x80900
	s_addc_u32 s19, s41, 0
	s_add_u32 s20, s40, 0x80a00
	s_addc_u32 s21, s41, 0
	s_add_u32 s22, s40, 0x80b00
	s_addc_u32 s23, s41, 0
	s_add_u32 s28, s40, 0x80c00
	s_addc_u32 s29, s41, 0
	s_add_u32 s30, s40, 0x80d00
	s_addc_u32 s31, s41, 0
	s_add_u32 s34, s40, 0x80e00
	s_addc_u32 s35, s41, 0
	s_add_u32 s36, s40, 0x80f00
	s_addc_u32 s37, s41, 0
	s_add_u32 s48, s40, 0x81000
	s_addc_u32 s49, s41, 0
	s_add_u32 s50, s40, 0x81100
	s_addc_u32 s51, s41, 0
	s_add_u32 s54, s40, 0x81200
	s_addc_u32 s55, s41, 0
	s_add_u32 s56, s40, 0x81300
	s_mul_i32 s24, s43, s92
	s_addc_u32 s57, s41, 0
	s_mul_i32 s24, s24, s42
	s_mov_b32 s25, 1
	s_mov_b64 s[6:7], 0
	s_waitcnt lgkmcnt(0)
	v_mov_b64_e32 v[0:1], s[8:9]
	v_mov_b64_e32 v[2:3], s[10:11]
	v_mov_b64_e32 v[4:5], s[12:13]
	v_mov_b64_e32 v[6:7], s[14:15]
	v_mov_b64_e32 v[8:9], s[16:17]
	v_mov_b64_e32 v[10:11], s[18:19]
	v_mov_b64_e32 v[12:13], s[20:21]
	v_mov_b64_e32 v[14:15], s[22:23]
	v_mov_b64_e32 v[16:17], s[28:29]
	v_mov_b64_e32 v[18:19], s[30:31]
	v_mov_b64_e32 v[20:21], s[34:35]
	v_mov_b64_e32 v[22:23], s[36:37]
	v_mov_b64_e32 v[24:25], s[48:49]
	v_mov_b64_e32 v[26:27], s[50:51]
	v_mov_b64_e32 v[28:29], s[54:55]
	v_mov_b64_e32 v[30:31], s[56:57]
	s_branch .LBB0_97

; #define GAS __attribute__((address_space(1)))
; __device__ __forceinline__ float wave_sum(float v) { return xrow_sum(row16_sum(v)); }
; __device__ __forceinline__ unsigned pk_bf16(float lo, float hi) { return pg8::cvt_pk_bf16(lo, hi); }
; template <bool HAS_F, bool HAS_H, bool XIN_B = false, bool XOUT_B = false> ...
;     ...
;     for (int row = row_lo; row < row_lo + RPW; ++row) {
;         f32x4 x[4]; u32x2 fwv[4];
; #pragma unroll
;         for (int j = 0; j < 4; ++j) { x[j] = xn[j]; if (HAS_F) fwv[j] = fn[j]; }
;         { const int rn = (row + 1 < row_lo + RPW) ? row + 1 : row;
; #pragma unroll
;           for (int j = 0; j < 4; ++j) { RP_LDX(xn[j], rn, j); if (HAS_F) fn[j] = __builtin_nontemporal_load((const GAS u32x2*)(Fb + (size_t)rn * DM + 256 * j + 4 * lane)); } }
;         if (HAS_F) {
;             f32x4 f[4]; float ss = 0.f;
; #pragma unroll
;             for (int j = 0; j < 4; ++j) { const u32x2 fw = fwv[j];
;                 f[j] = (f32x4){__uint_as_float(fw.x << 16), __uint_as_float(fw.x & 0xffff0000u), __uint_as_float(fw.y << 16), __uint_as_float(fw.y & 0xffff0000u)}; ss += (f[j].x * f[j].x + f[j].y * f[j].y) + (f[j].z * f[j].z + f[j].w * f[j].w); }
;             const float rstd = 1.0f / sqrtf(wave_sum(ss) * (1.0f / DM) + RMS_EPS);
; #pragma unroll
;             for (int j = 0; j < 4; ++j) { x[j] = x[j] + f[j] * rstd * Cg[j];
;                 if (XOUT_B) { u32x2 w; w.x = pk_bf16(x[j].x, x[j].y); w.y = pk_bf16(x[j].z, x[j].w); *(GAS u32x2*)(xoutb + (size_t)row * DM + 256 * j + 4 * lane) = w;
;                     x[j] = (f32x4){__uint_as_float(w.x << 16), __uint_as_float(w.x & 0xffff0000u), __uint_as_float(w.y << 16), __uint_as_float(w.y & 0xffff0000u)}; }
;                 else __builtin_nontemporal_store(x[j], (GAS f32x4*)(xout + (size_t)row * DM + 256 * j + 4 * lane)); }
;         }
.LBB0_264:
	v_lshl_add_u64 v[86:87], s[10:11], 0, v[32:33]
	s_add_i32 s6, s15, 1
	v_lshlrev_b32_e32 v70, 16, v72
	v_and_b32_e32 v71, 0xffff0000, v72
	v_lshlrev_b32_e32 v72, 16, v73
	v_and_b32_e32 v73, 0xffff0000, v73
	v_lshlrev_b32_e32 v74, 16, v76
	v_and_b32_e32 v75, 0xffff0000, v76
	v_lshlrev_b32_e32 v76, 16, v77
	v_and_b32_e32 v77, 0xffff0000, v77
	v_add_co_u32_e32 v106, vcc, s13, v86
	v_lshlrev_b32_e32 v78, 16, v80
	v_and_b32_e32 v79, 0xffff0000, v80
	v_lshlrev_b32_e32 v80, 16, v81
	v_and_b32_e32 v81, 0xffff0000, v81
	v_lshl_add_u64 v[90:91], s[8:9], 0, v[32:33]
	s_cmp_lt_i32 s15, s70
	v_mul_f32_e32 v92, v71, v71
	v_mul_f32_e32 v93, v73, v73
	v_mul_f32_e32 v94, v75, v75
	v_mul_f32_e32 v95, v77, v77
	v_addc_co_u32_e32 v107, vcc, 0, v87, vcc
	v_lshlrev_b32_e32 v82, 16, v84
	v_and_b32_e32 v83, 0xffff0000, v84
	v_lshlrev_b32_e32 v84, 16, v85
	v_and_b32_e32 v85, 0xffff0000, v85
	v_mul_f32_e32 v96, v79, v79
	v_mul_f32_e32 v97, v81, v81
	v_add_co_u32_e32 v86, vcc, s14, v90
	s_cselect_b64 s[4:5], -1, 0
	v_fmac_f32_e32 v92, v70, v70
	v_fmac_f32_e32 v93, v72, v72
	v_fmac_f32_e32 v94, v74, v74
	v_fmac_f32_e32 v95, v76, v76
	v_mul_f32_e32 v98, v83, v83
	v_mul_f32_e32 v99, v85, v85
	v_addc_co_u32_e32 v87, vcc, 0, v91, vcc
	v_fmac_f32_e32 v96, v78, v78
	v_fmac_f32_e32 v97, v80, v80
	s_and_b64 s[4:5], s[4:5], exec
	v_add_f32_e32 v90, v92, v93
	v_add_f32_e32 v91, v94, v95
	v_fmac_f32_e32 v98, v82, v82
	v_fmac_f32_e32 v99, v84, v84
	v_add_f32_e32 v92, v96, v97
	s_cselect_b32 s16, s6, s15
	v_add_f32_e32 v90, v91, v90
	v_add_f32_e32 v93, v98, v99
	s_ashr_i32 s17, s16, 31
	v_add_f32_e32 v90, v92, v90
	s_mov_b32 s15, s6
	s_lshl_b64 s[6:7], s[16:17], 12
	v_add_f32_e32 v90, v93, v90
	s_lshl_b64 s[16:17], s[16:17], 11
	v_lshl_add_u64 v[108:109], v[34:35], 0, s[6:7]
	v_add_f32_dpp v120, v90, v90 quad_perm:[1,0,3,2] row_mask:0xf bank_mask:0xf bound_ctrl:1
	v_lshl_add_u64 v[110:111], v[68:69], 0, s[16:17]
	s_mov_b64 exec, s[4:5]
	global_load_dwordx4 v[90:93], v[108:109], off nt
	global_load_dwordx4 v[94:97], v[108:109], off offset:1024 nt
	global_load_dwordx4 v[98:101], v[108:109], off offset:2048 nt
	global_load_dwordx4 v[102:105], v[108:109], off offset:3072 nt
	global_load_dwordx2 v[112:113], v[110:111], off nt
	global_load_dwordx2 v[114:115], v[110:111], off offset:512 nt
	global_load_dwordx2 v[116:117], v[110:111], off offset:1024 nt
	global_load_dwordx2 v[118:119], v[110:111], off offset:1536 nt
	s_mov_b64 exec, -1
	s_nop 4
	v_add_f32_dpp v108, v120, v120 quad_perm:[2,3,0,1] row_mask:0xf bank_mask:0xf bound_ctrl:1
	s_add_u32 s8, s8, 0x800
	s_addc_u32 s9, s9, 0
	v_add_f32_dpp v108, v108, v108 row_half_mirror row_mask:0xf bank_mask:0xf bound_ctrl:1
	s_add_u32 s10, s10, 0x800
	s_addc_u32 s11, s11, 0
	v_add_f32_dpp v108, v108, v108 row_mirror row_mask:0xf bank_mask:0xf bound_ctrl:1
	v_mov_b32_e32 v109, v108
	s_nop 1
	v_permlane16_swap_b32_e32 v108, v109
	v_add_f32_e32 v108, v108, v109
	v_mov_b32_e32 v109, v108
	s_nop 1
	v_permlane32_swap_b32_e32 v108, v109
	v_add_f32_e32 v108, v108, v109
	v_fmamk_f32 v108, v108, 0x3a800000, v88
	v_mul_f32_e32 v109, 0x4f800000, v108
	v_cmp_gt_f32_e32 vcc, s12, v108
	s_nop 1
	v_cndmask_b32_e32 v108, v108, v109, vcc
	v_sqrt_f32_e32 v109, v108
	s_nop 0
	v_add_u32_e32 v110, -1, v109
	v_add_u32_e32 v111, 1, v109
	v_fma_f32 v120, -v110, v109, v108
	v_fma_f32 v121, -v111, v109, v108
	v_cmp_ge_f32_e64 s[6:7], 0, v120
	s_nop 1
	v_cndmask_b32_e64 v109, v109, v110, s[6:7]
	v_cmp_lt_f32_e64 s[6:7], 0, v121
	s_nop 1
	v_cndmask_b32_e64 v109, v109, v111, s[6:7]
	v_mul_f32_e32 v110, 0x37800000, v109
	v_cndmask_b32_e32 v109, v109, v110, vcc
	v_cmp_class_f32_e32 vcc, v108, v89
	s_nop 1
	v_cndmask_b32_e32 v108, v109, v108, vcc
	v_div_scale_f32 v109, s[6:7], v108, v108, 1.0
	v_rcp_f32_e32 v111, v109
	v_div_scale_f32 v110, vcc, 1.0, v108, 1.0
	v_fma_f32 v120, -v109, v111, 1.0
	v_fmac_f32_e32 v111, v120, v111
	v_mul_f32_e32 v120, v110, v111
	v_fma_f32 v121, -v109, v120, v110
	v_fmac_f32_e32 v120, v121, v111
	v_fma_f32 v109, -v109, v120, v110
	v_div_fmas_f32 v109, v109, v111, v120
	v_div_fixup_f32 v108, v109, v108, 1.0
	v_pk_mul_f32 v[70:71], v[70:71], v[108:109] op_sel_hi:[1,0]
	v_pk_mul_f32 v[72:73], v[72:73], v[108:109] op_sel_hi:[1,0]
	v_pk_fma_f32 v[16:17], v[38:39], v[70:71], v[16:17]
	v_pk_mul_f32 v[74:75], v[74:75], v[108:109] op_sel_hi:[1,0]
	v_pk_mul_f32 v[76:77], v[76:77], v[108:109] op_sel_hi:[1,0]
	v_pk_fma_f32 v[18:19], v[36:37], v[72:73], v[18:19]
	v_cvt_pk_bf16_f32 v16, v16, v17
	v_pk_mul_f32 v[78:79], v[78:79], v[108:109] op_sel_hi:[1,0]
	v_cvt_pk_bf16_f32 v17, v18, v19
	v_pk_mul_f32 v[80:81], v[80:81], v[108:109] op_sel_hi:[1,0]
	v_pk_mul_f32 v[82:83], v[82:83], v[108:109] op_sel_hi:[1,0]
	v_pk_fma_f32 v[22:23], v[40:41], v[76:77], v[22:23]
	v_pk_fma_f32 v[20:21], v[42:43], v[74:75], v[20:21]
	global_store_dwordx2 v[106:107], v[16:17], off sc1
	v_lshlrev_b32_e32 v70, 16, v16
	v_and_b32_e32 v71, 0xffff0000, v16
	v_lshlrev_b32_e32 v74, 16, v17
	v_and_b32_e32 v75, 0xffff0000, v17
	v_cvt_pk_bf16_f32 v16, v20, v21
	v_cvt_pk_bf16_f32 v17, v22, v23
	v_pk_mul_f32 v[84:85], v[84:85], v[108:109] op_sel_hi:[1,0]
	v_pk_fma_f32 v[26:27], v[64:65], v[80:81], v[26:27]
	v_pk_fma_f32 v[24:25], v[66:67], v[78:79], v[24:25]
	v_pk_fma_f32 v[28:29], v[46:47], v[82:83], v[28:29]
	global_store_dwordx2 v[106:107], v[16:17], off offset:512 sc1
	v_lshlrev_b32_e32 v78, 16, v16
	v_and_b32_e32 v79, 0xffff0000, v16
	v_lshlrev_b32_e32 v82, 16, v17
	v_and_b32_e32 v83, 0xffff0000, v17
	v_cvt_pk_bf16_f32 v16, v24, v25
	v_cvt_pk_bf16_f32 v17, v26, v27
	v_mul_f32_e32 v18, v71, v71
	v_mul_f32_e32 v19, v75, v75
	v_pk_fma_f32 v[30:31], v[44:45], v[84:85], v[30:31]
	global_store_dwordx2 v[106:107], v[16:17], off offset:1024 sc1
	v_lshlrev_b32_e32 v108, 16, v16
	v_and_b32_e32 v109, 0xffff0000, v16
	v_lshlrev_b32_e32 v110, 16, v17
	v_and_b32_e32 v111, 0xffff0000, v17
	v_cvt_pk_bf16_f32 v16, v28, v29
	v_cvt_pk_bf16_f32 v17, v30, v31
	v_fmac_f32_e32 v18, v70, v70
	v_fmac_f32_e32 v19, v74, v74
	v_mul_f32_e32 v20, v79, v79
	v_mul_f32_e32 v21, v83, v83
	global_store_dwordx2 v[106:107], v[16:17], off offset:1536 sc1
	v_lshlrev_b32_e32 v106, 16, v16
	v_and_b32_e32 v107, 0xffff0000, v16
	v_lshlrev_b32_e32 v120, 16, v17
	v_and_b32_e32 v121, 0xffff0000, v17
	v_add_f32_e32 v16, v18, v19
	v_fmac_f32_e32 v20, v78, v78
	v_fmac_f32_e32 v21, v82, v82
	v_mul_f32_e32 v17, v109, v109
	v_mul_f32_e32 v18, v111, v111
	v_add_f32_e32 v19, v20, v21
	v_fmac_f32_e32 v17, v108, v108
	v_fmac_f32_e32 v18, v110, v110
	v_mul_f32_e32 v20, v107, v107
	v_mul_f32_e32 v21, v121, v121
	v_add_f32_e32 v16, v16, v19
	v_add_f32_e32 v17, v17, v18
	v_fmac_f32_e32 v20, v106, v106
	v_fmac_f32_e32 v21, v120, v120
	v_add_f32_e32 v16, v16, v17
	v_add_f32_e32 v17, v20, v21
	v_add_f32_e32 v16, v16, v17
	s_waitcnt vmcnt(9)
; #define GAS __attribute__((address_space(1)))
; __device__ __forceinline__ float wave_sum(float v) { return xrow_sum(row16_sum(v)); }
; __device__ __forceinline__ unsigned pk_bf16(float lo, float hi) { return pg8::cvt_pk_bf16(lo, hi); }
; __device__ __forceinline__ void xcd_barrier(const XcdBarrier& b) {
;     asm volatile("s_waitcnt vmcnt(0)" ::: "memory");
;     __syncthreads();
;     if (threadIdx.x == 0) {
;         unsigned* bar = b.bar;
;         __builtin_amdgcn_s_waitcnt(0);
;         unsigned nloc = b.st[0], nx = b.st[1];
;         if (nloc == 0u) { xcd_barrier_complete(bar, b.x, nloc, nx); b.st[0] = nloc; b.st[1] = nx; }
; template <bool HAS_F, bool HAS_H, bool XIN_B = false, bool XOUT_B = false> ...
;     ...
;         if (HAS_H) {
;             float ss = 0.f;
; #pragma unroll
;             for (int j = 0; j < 4; ++j) ss += (x[j].x * x[j].x + x[j].y * x[j].y) + (x[j].z * x[j].z + x[j].w * x[j].w);
;             const float rstd = 1.0f / sqrtf(wave_sum(ss) * (1.0f / DM) + RMS_EPS);
; #pragma unroll
;             for (int j = 0; j < 4; ++j) { const f32x4 h = x[j] * rstd * A[j] + Sh[j]; u32x2 w; w.x = pk_bf16(h.x, h.y); w.y = pk_bf16(h.z, h.w);
;                 *(GAS u32x2*)(H + (size_t)row * DM + 256 * j + 4 * lane) = w; }
	v_mov_b64_e32 v[24:25], v[98:99]
	s_waitcnt vmcnt(8)
	v_mov_b64_e32 v[28:29], v[102:103]
	v_add_f32_dpp v16, v16, v16 quad_perm:[1,0,3,2] row_mask:0xf bank_mask:0xf bound_ctrl:1
	s_waitcnt vmcnt(4)
	v_mov_b64_e32 v[84:85], v[118:119]
	v_mov_b64_e32 v[80:81], v[116:117]
	v_add_f32_dpp v16, v16, v16 quad_perm:[2,3,0,1] row_mask:0xf bank_mask:0xf bound_ctrl:1
	v_mov_b64_e32 v[76:77], v[114:115]
	v_mov_b64_e32 v[72:73], v[112:113]
	v_add_f32_dpp v16, v16, v16 row_half_mirror row_mask:0xf bank_mask:0xf bound_ctrl:1
	v_mov_b64_e32 v[26:27], v[100:101]
	v_mov_b64_e32 v[30:31], v[104:105]
	v_add_f32_dpp v16, v16, v16 row_mirror row_mask:0xf bank_mask:0xf bound_ctrl:1
	v_mov_b32_e32 v17, v16
	s_nop 1
	v_permlane16_swap_b32_e32 v16, v17
	v_add_f32_e32 v16, v16, v17
	v_mov_b32_e32 v17, v16
	s_nop 1
	v_permlane32_swap_b32_e32 v16, v17
	v_add_f32_e32 v16, v16, v17
	v_fmamk_f32 v16, v16, 0x3a800000, v88
	v_mul_f32_e32 v17, 0x4f800000, v16
	v_cmp_gt_f32_e32 vcc, s12, v16
	s_nop 1
	v_cndmask_b32_e32 v16, v16, v17, vcc
	v_sqrt_f32_e32 v17, v16
	s_nop 0
	v_add_u32_e32 v18, -1, v17
	v_add_u32_e32 v19, 1, v17
	v_fma_f32 v20, -v18, v17, v16
	v_fma_f32 v21, -v19, v17, v16
	v_cmp_ge_f32_e64 s[6:7], 0, v20
	s_nop 1
	v_cndmask_b32_e64 v17, v17, v18, s[6:7]
	v_cmp_lt_f32_e64 s[6:7], 0, v21
	v_mov_b64_e32 v[20:21], v[94:95]
	v_mov_b64_e32 v[22:23], v[96:97]
	v_cndmask_b32_e64 v17, v17, v19, s[6:7]
	v_mul_f32_e32 v18, 0x37800000, v17
	v_cndmask_b32_e32 v17, v17, v18, vcc
	v_cmp_class_f32_e32 vcc, v16, v89
	s_nop 1
	v_cndmask_b32_e32 v122, v17, v16, vcc
	v_div_scale_f32 v123, s[6:7], v122, v122, 1.0
	v_rcp_f32_e32 v125, v123
	v_div_scale_f32 v124, vcc, 1.0, v122, 1.0
	v_fma_f32 v16, -v123, v125, 1.0
	v_fmac_f32_e32 v125, v16, v125
	v_mul_f32_e32 v126, v124, v125
	v_fma_f32 v16, -v123, v126, v124
	v_fmac_f32_e32 v126, v16, v125
	v_mov_b64_e32 v[16:17], v[90:91]
	v_mov_b64_e32 v[18:19], v[92:93]
	v_fma_f32 v90, -v123, v126, v124
	v_div_fmas_f32 v90, v90, v125, v126
	v_div_fixup_f32 v90, v90, v122, 1.0
	v_pk_mul_f32 v[70:71], v[70:71], v[90:91] op_sel_hi:[1,0]
	v_pk_mul_f32 v[74:75], v[74:75], v[90:91] op_sel_hi:[1,0]
	v_pk_fma_f32 v[70:71], v[50:51], v[70:71], v[12:13]
	v_pk_mul_f32 v[78:79], v[78:79], v[90:91] op_sel_hi:[1,0]
	v_pk_mul_f32 v[82:83], v[82:83], v[90:91] op_sel_hi:[1,0]
	v_pk_fma_f32 v[74:75], v[48:49], v[74:75], v[14:15]
	v_cvt_pk_bf16_f32 v70, v70, v71
	v_pk_mul_f32 v[92:93], v[108:109], v[90:91] op_sel_hi:[1,0]
	v_cvt_pk_bf16_f32 v71, v74, v75
	v_pk_mul_f32 v[94:95], v[110:111], v[90:91] op_sel_hi:[1,0]
	v_pk_fma_f32 v[82:83], v[52:53], v[82:83], v[2:3]
	v_pk_fma_f32 v[78:79], v[54:55], v[78:79], v[0:1]
	global_store_dwordx2 v[86:87], v[70:71], off sc1
	v_cvt_pk_bf16_f32 v70, v78, v79
	v_cvt_pk_bf16_f32 v71, v82, v83
	v_pk_mul_f32 v[96:97], v[106:107], v[90:91] op_sel_hi:[1,0]
	v_pk_mul_f32 v[90:91], v[120:121], v[90:91] op_sel_hi:[1,0]
	v_pk_fma_f32 v[94:95], v[56:57], v[94:95], v[6:7]
	v_pk_fma_f32 v[92:93], v[58:59], v[92:93], v[4:5]
	global_store_dwordx2 v[86:87], v[70:71], off offset:512 sc1
	v_cvt_pk_bf16_f32 v70, v92, v93
	v_cvt_pk_bf16_f32 v71, v94, v95
	s_mov_b64 vcc, s[4:5]
	v_pk_fma_f32 v[90:91], v[60:61], v[90:91], v[10:11]
	v_pk_fma_f32 v[96:97], v[62:63], v[96:97], v[8:9]
	global_store_dwordx2 v[86:87], v[70:71], off offset:1024 sc1
	v_cvt_pk_bf16_f32 v70, v96, v97
	v_cvt_pk_bf16_f32 v71, v90, v91
	global_store_dwordx2 v[86:87], v[70:71], off offset:1536 sc1
	s_cbranch_vccnz .LBB0_264
	s_waitcnt vmcnt(0)
	s_barrier
	s_and_saveexec_b64 s[4:5], s[26:27]
	s_xor_b64 s[38:39], exec, s[4:5]
	s_cbranch_execz .LBB0_310
	s_add_i32 s4, 0, 0x20020
	v_mov_b32_e32 v0, s4
	s_waitcnt vmcnt(0) expcnt(0) lgkmcnt(0)
	ds_read_b32 v2, v0
	s_add_i32 s4, 0, 0x20024
	v_mov_b32_e32 v0, s4
	ds_read_b32 v0, v0
	s_waitcnt lgkmcnt(1)
	v_cmp_ne_u32_e32 vcc, 0, v2
	s_cbranch_vccnz .LBB0_280
	s_add_u32 s4, s40, 0x80200
	s_addc_u32 s5, s41, 0
	s_add_u32 s8, s40, 0x80400
	s_addc_u32 s9, s41, 0
	s_add_u32 s10, s40, 0x80500
	s_addc_u32 s11, s41, 0
	s_add_u32 s12, s40, 0x80600
	s_addc_u32 s13, s41, 0
	s_add_u32 s14, s40, 0x80700
	s_addc_u32 s15, s41, 0
	s_add_u32 s16, s40, 0x80800
	s_addc_u32 s17, s41, 0
	s_add_u32 s18, s40, 0x80900
	s_addc_u32 s19, s41, 0
	s_add_u32 s20, s40, 0x80a00
	s_addc_u32 s21, s41, 0
	s_add_u32 s22, s40, 0x80b00
	s_addc_u32 s23, s41, 0
	s_add_u32 s28, s40, 0x80c00
	s_addc_u32 s29, s41, 0
	s_add_u32 s30, s40, 0x80d00
	s_addc_u32 s31, s41, 0
	s_add_u32 s34, s40, 0x80e00
	s_addc_u32 s35, s41, 0
	s_add_u32 s36, s40, 0x80f00
	s_addc_u32 s37, s41, 0
	s_add_u32 s56, s40, 0x81000
	s_addc_u32 s57, s41, 0
	s_add_u32 s58, s40, 0x81100
	s_addc_u32 s59, s41, 0
	s_add_u32 s60, s40, 0x81200
	s_addc_u32 s61, s41, 0
	s_add_u32 s62, s40, 0x81300
	s_mul_i32 s24, s43, s92
	s_addc_u32 s63, s41, 0
	s_mul_i32 s24, s24, s42
	s_mov_b32 s25, 1
	s_mov_b64 s[6:7], 0
	s_waitcnt lgkmcnt(0)
	v_mov_b64_e32 v[0:1], s[8:9]
	v_mov_b64_e32 v[2:3], s[10:11]
	v_mov_b64_e32 v[4:5], s[12:13]
	v_mov_b64_e32 v[6:7], s[14:15]
	v_mov_b64_e32 v[8:9], s[16:17]
	v_mov_b64_e32 v[10:11], s[18:19]
	v_mov_b64_e32 v[12:13], s[20:21]
	v_mov_b64_e32 v[14:15], s[22:23]
	v_mov_b64_e32 v[16:17], s[28:29]
	v_mov_b64_e32 v[18:19], s[30:31]
	v_mov_b64_e32 v[20:21], s[34:35]
	v_mov_b64_e32 v[22:23], s[36:37]
	v_mov_b64_e32 v[24:25], s[56:57]
	v_mov_b64_e32 v[26:27], s[58:59]
	v_mov_b64_e32 v[28:29], s[60:61]
	v_mov_b64_e32 v[30:31], s[62:63]
	s_branch .LBB0_270

; #define GAS __attribute__((address_space(1)))
; __device__ __forceinline__ float wave_sum(float v) { return xrow_sum(row16_sum(v)); }
; __device__ __forceinline__ unsigned pk_bf16(float lo, float hi) { return pg8::cvt_pk_bf16(lo, hi); }
; __device__ __forceinline__ void rowpass_attn(const float* __restrict__ Od, const bf16* __restrict__ Os, bf16* __restrict__ H, const float* __restrict__ subln,
;                                              const float* __restrict__ sbeta, float lam, int gw, int lane) {
;     ...
;     for (int row = row_lo; row < row_lo + RPW; ++row) {
;         const u32x4 w0 = n0, w1 = n1, ws = ns;
;         { const int rn = (row + 1 < row_lo + RPW) ? row + 1 : row;
;           n0 = __builtin_nontemporal_load((const GAS u32x4*)((const bf16*)Od + (size_t)rn * 1024 + hd * 256 + e0)); n1 = __builtin_nontemporal_load((const GAS u32x4*)((const bf16*)Od + (size_t)rn * 1024 + hd * 256 + 128 + e0));
;           ns = __builtin_nontemporal_load((const GAS u32x4*)(Os + (size_t)rn * 512 + 8 * lane)); }
;         float a0[8], a1[8], v[8], sv[8];
;         RA_UNPK(w0, a0); RA_UNPK(w1, a1); RA_UNPK(ws, sv);
;         float ss = 0.f, s2 = 0.f;
; #pragma unroll
;         for (int i = 0; i < 8; ++i) { v[i] = a0[i] - a1[i] * lam; ss += v[i] * v[i]; s2 += sv[i] * sv[i]; }
;         ss = row16_sum(ss);
;         const float rstd = 0.8f / sqrtf(ss * (1.0f / 128.0f) + RMS_EPS);
;         u32x4 od; od.x = pk_bf16(v[0] * rstd * sl0.x, v[1] * rstd * sl0.y); od.y = pk_bf16(v[2] * rstd * sl0.z, v[3] * rstd * sl0.w);
;         od.z = pk_bf16(v[4] * rstd * sl1.x, v[5] * rstd * sl1.y); od.w = pk_bf16(v[6] * rstd * sl1.z, v[7] * rstd * sl1.w);
;         *(GAS u32x4*)(H + (size_t)row * 1024 + hd * 128 + e0) = od;
;         const float rstd2 = 1.0f / sqrtf(wave_sum(s2) * (1.0f / 512.0f) + RMS_EPS);
;         u32x4 o; o.x = pk_bf16(sv[0] * rstd2 * be0.x, sv[1] * rstd2 * be0.y); o.y = pk_bf16(sv[2] * rstd2 * be0.z, sv[3] * rstd2 * be0.w);
;         o.z = pk_bf16(sv[4] * rstd2 * be1.x, sv[5] * rstd2 * be1.y); o.w = pk_bf16(sv[6] * rstd2 * be1.z, sv[7] * rstd2 * be1.w);
;         *(GAS u32x4*)(H + (size_t)row * 1024 + 512 + 8 * lane) = o;
;     }
.LBB0_525:
	s_add_i32 s7, s14, 1
	s_cmp_lt_i32 s14, s70
	s_cselect_b64 s[4:5], -1, 0
	s_and_b64 s[4:5], s[4:5], exec
	s_cselect_b32 s6, s7, s14
	s_mov_b32 s14, s7
	s_ashr_i32 s7, s6, 31
	s_waitcnt vmcnt(0)
	v_lshlrev_b32_e32 v40, 16, v25
	v_lshlrev_b32_e32 v41, 16, v26
	v_lshlrev_b32_e32 v44, 16, v17
	v_lshlrev_b32_e32 v45, 16, v18
	s_lshl_b64 s[8:9], s[6:7], 11
	v_lshlrev_b32_e32 v39, 16, v24
	v_and_b32_e32 v24, 0xffff0000, v24
	v_and_b32_e32 v25, 0xffff0000, v25
	v_and_b32_e32 v26, 0xffff0000, v26
	v_lshlrev_b32_e32 v42, 16, v27
	v_and_b32_e32 v27, 0xffff0000, v27
	v_lshlrev_b32_e32 v43, 16, v16
	v_and_b32_e32 v16, 0xffff0000, v16
	v_and_b32_e32 v17, 0xffff0000, v17
	v_and_b32_e32 v18, 0xffff0000, v18
	v_lshlrev_b32_e32 v46, 16, v19
	v_and_b32_e32 v19, 0xffff0000, v19
	s_waitcnt lgkmcnt(0)
	v_fma_f32 v44, -v36, v44, v40
	v_fma_f32 v45, -v36, v45, v41
	s_lshl_b64 s[6:7], s[6:7], 10
	v_lshl_add_u64 v[40:41], v[30:31], 0, s[8:9]
	v_lshlrev_b32_e32 v47, 16, v20
	v_and_b32_e32 v48, 0xffff0000, v20
	v_lshlrev_b32_e32 v49, 16, v21
	v_and_b32_e32 v50, 0xffff0000, v21
	v_lshlrev_b32_e32 v51, 16, v22
	v_and_b32_e32 v52, 0xffff0000, v22
	v_lshlrev_b32_e32 v53, 16, v23
	v_and_b32_e32 v54, 0xffff0000, v23
	v_fma_f32 v39, -v36, v43, v39
	v_fma_f32 v55, -v36, v16, v24
	v_fma_f32 v57, -v36, v17, v25
	v_fma_f32 v58, -v36, v18, v26
	v_fma_f32 v46, -v36, v46, v42
	v_fma_f32 v59, -v36, v19, v27
	v_lshl_add_u64 v[42:43], v[28:29], 0, s[6:7]
	s_mov_b64 exec, s[4:5]
	global_load_dwordx4 v[24:27], v[40:41], off nt
	global_load_dwordx4 v[16:19], v[40:41], off offset:256 nt
	global_load_dwordx4 v[20:23], v[42:43], off nt
	s_mov_b64 exec, -1
	s_nop 4
	v_mul_f32_e32 v56, v48, v48
	v_mul_f32_e32 v60, v55, v55
	v_fmac_f32_e32 v56, v47, v47
	v_fmac_f32_e32 v60, v39, v39
	v_fmac_f32_e32 v56, v49, v49
	v_fmac_f32_e32 v60, v44, v44
	v_fmac_f32_e32 v56, v50, v50
	v_fmac_f32_e32 v60, v57, v57
	v_fmac_f32_e32 v56, v51, v51
	v_fmac_f32_e32 v60, v45, v45
	v_fmac_f32_e32 v56, v52, v52
	v_fmac_f32_e32 v60, v58, v58
	v_fmac_f32_e32 v56, v53, v53
	v_fmac_f32_e32 v60, v46, v46
	v_fmac_f32_e32 v56, v54, v54
	v_fmac_f32_e32 v60, v59, v59
	s_nop 0
	v_add_f32_dpp v40, v56, v56 quad_perm:[1,0,3,2] row_mask:0xf bank_mask:0xf bound_ctrl:1
	v_add_f32_dpp v41, v60, v60 quad_perm:[1,0,3,2] row_mask:0xf bank_mask:0xf bound_ctrl:1
	s_nop 0
	v_add_f32_dpp v40, v40, v40 quad_perm:[2,3,0,1] row_mask:0xf bank_mask:0xf bound_ctrl:1
	v_add_f32_dpp v41, v41, v41 quad_perm:[2,3,0,1] row_mask:0xf bank_mask:0xf bound_ctrl:1
	s_nop 0
	v_add_f32_dpp v40, v40, v40 row_half_mirror row_mask:0xf bank_mask:0xf bound_ctrl:1
	v_add_f32_dpp v41, v41, v41 row_half_mirror row_mask:0xf bank_mask:0xf bound_ctrl:1
	s_nop 0
	v_add_f32_dpp v40, v40, v40 row_mirror row_mask:0xf bank_mask:0xf bound_ctrl:1
	v_add_f32_dpp v41, v41, v41 row_mirror row_mask:0xf bank_mask:0xf bound_ctrl:1
	v_mov_b32_e32 v42, v40
	v_fmamk_f32 v41, v41, 0x3c000000, v37
	s_nop 0
	v_permlane16_swap_b32_e32 v40, v42
	v_mul_f32_e32 v43, 0x4f800000, v41
	v_cmp_gt_f32_e32 vcc, s12, v41
	v_add_f32_e32 v40, v40, v42
	v_mov_b32_e32 v42, v40
	v_cndmask_b32_e32 v41, v41, v43, vcc
	v_sqrt_f32_e32 v43, v41
	v_permlane32_swap_b32_e32 v40, v42
	v_add_f32_e32 v40, v40, v42
	v_fmamk_f32 v40, v40, 0x3b000000, v37
	v_mul_f32_e32 v42, 0x4f800000, v40
	v_cmp_gt_f32_e64 s[6:7], s12, v40
	v_add_u32_e32 v56, -1, v43
	v_add_u32_e32 v60, 1, v43
	v_cndmask_b32_e64 v40, v40, v42, s[6:7]
	v_fma_f32 v42, -v56, v43, v41
	v_fma_f32 v61, -v60, v43, v41
	v_cmp_ge_f32_e64 s[8:9], 0, v42
	v_sqrt_f32_e32 v62, v40
	s_nop 0
	v_cndmask_b32_e64 v42, v43, v56, s[8:9]
	v_cmp_lt_f32_e64 s[8:9], 0, v61
	v_add_u32_e32 v56, 1, v62
	s_nop 0
	v_cndmask_b32_e64 v42, v42, v60, s[8:9]
	v_mul_f32_e32 v43, 0x37800000, v42
	v_cndmask_b32_e32 v42, v42, v43, vcc
	v_cmp_class_f32_e32 vcc, v41, v38
	v_add_u32_e32 v43, -1, v62
	v_fma_f32 v60, -v56, v62, v40
	v_cndmask_b32_e32 v41, v42, v41, vcc
	v_fma_f32 v42, -v43, v62, v40
	v_div_scale_f32 v61, s[8:9], v41, v41, s13
	v_cmp_ge_f32_e64 s[8:9], 0, v42
	v_div_scale_f32 v63, vcc, s13, v41, s13
	s_nop 0
	v_cndmask_b32_e64 v42, v62, v43, s[8:9]
	v_cmp_lt_f32_e64 s[8:9], 0, v60
	v_rcp_f32_e32 v43, v61
	s_nop 0
	v_cndmask_b32_e64 v42, v42, v56, s[8:9]
	v_mul_f32_e32 v56, 0x37800000, v42
	v_cndmask_b32_e64 v42, v42, v56, s[6:7]
	v_cmp_class_f32_e64 s[6:7], v40, v38
	s_nop 1
	v_cndmask_b32_e64 v56, v42, v40, s[6:7]
	v_fma_f32 v40, -v61, v43, 1.0
	v_div_scale_f32 v60, s[6:7], v56, v56, 1.0
	v_fmac_f32_e32 v43, v40, v43
	v_rcp_f32_e32 v64, v60
	v_mul_f32_e32 v40, v63, v43
	v_fma_f32 v42, -v61, v40, v63
	v_fmac_f32_e32 v40, v42, v43
	v_fma_f32 v42, -v61, v40, v63
	v_fma_f32 v61, -v60, v64, 1.0
	v_div_scale_f32 v62, s[6:7], 1.0, v56, 1.0
	v_div_fmas_f32 v40, v42, v43, v40
	v_fmac_f32_e32 v64, v61, v64
	v_div_fixup_f32 v40, v40, v41, s13
	v_mul_f32_e32 v61, v62, v64
	v_mul_f32_e32 v39, v39, v40
	v_mul_f32_e32 v41, v55, v40
	v_fma_f32 v55, -v60, v61, v62
	v_mul_f32_e32 v42, v44, v40
	v_mul_f32_e32 v43, v57, v40
	v_mul_f32_e32 v44, v45, v40
	v_mul_f32_e32 v45, v58, v40
	v_mul_f32_e32 v46, v46, v40
	v_mul_f32_e32 v40, v59, v40
	v_mul_f32_e32 v39, v0, v39
	v_fmac_f32_e32 v61, v55, v64
	v_mul_f32_e32 v41, v1, v41
	v_mul_f32_e32 v57, v7, v40
	v_cvt_pk_bf16_f32 v40, v39, v41
	v_fma_f32 v39, -v60, v61, v62
	s_mov_b64 vcc, s[6:7]
	v_mul_f32_e32 v42, v2, v42
	v_mul_f32_e32 v43, v3, v43
	v_div_fmas_f32 v39, v39, v64, v61
	v_mul_f32_e32 v44, v4, v44
	v_mul_f32_e32 v45, v5, v45
	v_mul_f32_e32 v46, v6, v46
	v_cvt_pk_bf16_f32 v41, v42, v43
	v_cvt_pk_bf16_f32 v42, v44, v45
	v_cvt_pk_bf16_f32 v43, v46, v57
	v_div_fixup_f32 v39, v39, v56, 1.0
	global_store_dwordx4 v[34:35], v[40:43], off sc1
	v_mul_f32_e32 v44, v39, v51
	v_mul_f32_e32 v45, v39, v52
	v_mul_f32_e32 v40, v39, v47
	v_mul_f32_e32 v41, v39, v48
	v_mul_f32_e32 v42, v39, v49
	v_mul_f32_e32 v43, v39, v50
	v_mul_f32_e32 v46, v39, v53
	v_mul_f32_e32 v39, v39, v54
	v_mul_f32_e32 v40, v8, v40
	v_mul_f32_e32 v41, v9, v41
	v_mul_f32_e32 v42, v10, v42
	v_mul_f32_e32 v43, v11, v43
	v_lshl_add_u64 v[34:35], v[34:35], 0, s[10:11]
	v_mul_f32_e32 v44, v12, v44
	v_mul_f32_e32 v45, v13, v45
	v_mul_f32_e32 v46, v14, v46
	v_mul_f32_e32 v39, v15, v39
	v_cvt_pk_bf16_f32 v40, v40, v41
	v_cvt_pk_bf16_f32 v41, v42, v43
	v_cvt_pk_bf16_f32 v42, v44, v45
	v_cvt_pk_bf16_f32 v43, v46, v39
	global_store_dwordx4 v[32:33], v[40:43], off sc1
	v_lshl_add_u64 v[32:33], v[32:33], 0, s[10:11]
	s_mov_b64 vcc, s[4:5]
	s_cbranch_vccnz .LBB0_525
; __device__ __forceinline__ unsigned xb_ld(unsigned* p)              { return __hip_atomic_load(p, __ATOMIC_RELAXED, __HIP_MEMORY_SCOPE_AGENT); }
; __device__ __forceinline__ void xcd_barrier_complete(unsigned* bar, unsigned x, unsigned& nloc, unsigned& nx) {
;     const unsigned G = gridDim.x * gridDim.y * gridDim.z;
;     unsigned sum, cnt, mine, sp = 0u;
;     for (;;) {
;         sum = 0u; cnt = 0u; mine = 0u;
; #pragma unroll
;         for (unsigned j = 0; j < 16; ++j) { const unsigned c = xb_ld(&bar[XB_XCNT(j)]); sum += c; cnt += (c > 0u) ? 1u : 0u; mine = (j == x) ? c : mine; }
; __device__ __forceinline__ void xcd_barrier(const XcdBarrier& b) {
;     asm volatile("s_waitcnt vmcnt(0)" ::: "memory");
;     __syncthreads();
;     if (threadIdx.x == 0) {
;         unsigned* bar = b.bar;
;         __builtin_amdgcn_s_waitcnt(0);
;         unsigned nloc = b.st[0], nx = b.st[1];
;         if (nloc == 0u) { xcd_barrier_complete(bar, b.x, nloc, nx); b.st[0] = nloc; b.st[1] = nx; }
	s_waitcnt vmcnt(0)
	s_barrier
	s_and_saveexec_b64 s[4:5], s[26:27]
	s_xor_b64 s[38:39], exec, s[4:5]
	s_cbranch_execz .LBB0_571
	s_add_i32 s3, 0, 0x20020
	v_mov_b32_e32 v0, s3
	s_waitcnt vmcnt(0) expcnt(0) lgkmcnt(0)
	ds_read_b32 v2, v0
	s_add_i32 s3, 0, 0x20024
	v_mov_b32_e32 v0, s3
	ds_read_b32 v0, v0
	s_waitcnt lgkmcnt(1)
	v_cmp_ne_u32_e32 vcc, 0, v2
	s_cbranch_vccnz .LBB0_541
	s_add_u32 s4, s40, 0x80200
	s_addc_u32 s5, s41, 0
	s_add_u32 s8, s40, 0x80400
	s_addc_u32 s9, s41, 0
	s_add_u32 s10, s40, 0x80500
	s_addc_u32 s11, s41, 0
	s_add_u32 s12, s40, 0x80600
	s_addc_u32 s13, s41, 0
	s_add_u32 s14, s40, 0x80700
	s_addc_u32 s15, s41, 0
	s_add_u32 s16, s40, 0x80800
	s_addc_u32 s17, s41, 0
	s_add_u32 s18, s40, 0x80900
	s_addc_u32 s19, s41, 0
	s_add_u32 s20, s40, 0x80a00
	s_addc_u32 s21, s41, 0
	s_add_u32 s22, s40, 0x80b00
	s_addc_u32 s23, s41, 0
	s_add_u32 s28, s40, 0x80c00
	s_addc_u32 s29, s41, 0
	s_add_u32 s30, s40, 0x80d00
	s_addc_u32 s31, s41, 0
	s_add_u32 s34, s40, 0x80e00
	s_addc_u32 s35, s41, 0
	s_add_u32 s36, s40, 0x80f00
	s_addc_u32 s37, s41, 0
	s_add_u32 s48, s40, 0x81000
	s_addc_u32 s49, s41, 0
	s_add_u32 s56, s40, 0x81100
	s_addc_u32 s57, s41, 0
	s_add_u32 s58, s40, 0x81200
	s_addc_u32 s59, s41, 0
	s_add_u32 s60, s40, 0x81300
	s_mul_i32 s24, s43, s92
	s_addc_u32 s61, s41, 0
	s_mul_i32 s24, s24, s42
	s_mov_b32 s25, 1
	s_mov_b64 s[6:7], 0
	s_waitcnt lgkmcnt(0)
	v_mov_b64_e32 v[0:1], s[8:9]
	v_mov_b64_e32 v[2:3], s[10:11]
	v_mov_b64_e32 v[4:5], s[12:13]
	v_mov_b64_e32 v[6:7], s[14:15]
	v_mov_b64_e32 v[8:9], s[16:17]
	v_mov_b64_e32 v[10:11], s[18:19]
	v_mov_b64_e32 v[12:13], s[20:21]
	v_mov_b64_e32 v[14:15], s[22:23]
	v_mov_b64_e32 v[16:17], s[28:29]
	v_mov_b64_e32 v[18:19], s[30:31]
	v_mov_b64_e32 v[20:21], s[34:35]
	v_mov_b64_e32 v[22:23], s[36:37]
	v_mov_b64_e32 v[24:25], s[48:49]
	v_mov_b64_e32 v[26:27], s[56:57]
	v_mov_b64_e32 v[28:29], s[58:59]
	v_mov_b64_e32 v[30:31], s[60:61]
	s_branch .LBB0_531

; #define GAS __attribute__((address_space(1)))
; __device__ __forceinline__ float wave_sum(float v) { return xrow_sum(row16_sum(v)); }
; __device__ __forceinline__ unsigned pk_bf16(float lo, float hi) { return pg8::cvt_pk_bf16(lo, hi); }
; template <bool HAS_F, bool HAS_H, bool XIN_B = false, bool XOUT_B = false> ...
;     ...
;     for (int row = row_lo; row < row_lo + RPW; ++row) {
;         f32x4 x[4]; u32x2 fwv[4];
; #pragma unroll
;         for (int j = 0; j < 4; ++j) { x[j] = xn[j]; if (HAS_F) fwv[j] = fn[j]; }
;         { const int rn = (row + 1 < row_lo + RPW) ? row + 1 : row;
; #pragma unroll
;           for (int j = 0; j < 4; ++j) { RP_LDX(xn[j], rn, j); if (HAS_F) fn[j] = __builtin_nontemporal_load((const GAS u32x2*)(Fb + (size_t)rn * DM + 256 * j + 4 * lane)); } }
;         if (HAS_F) {
;             f32x4 f[4]; float ss = 0.f;
; #pragma unroll
;             for (int j = 0; j < 4; ++j) { const u32x2 fw = fwv[j];
;                 f[j] = (f32x4){__uint_as_float(fw.x << 16), __uint_as_float(fw.x & 0xffff0000u), __uint_as_float(fw.y << 16), __uint_as_float(fw.y & 0xffff0000u)}; ss += (f[j].x * f[j].x + f[j].y * f[j].y) + (f[j].z * f[j].z + f[j].w * f[j].w); }
;             const float rstd = 1.0f / sqrtf(wave_sum(ss) * (1.0f / DM) + RMS_EPS);
; #pragma unroll
;             for (int j = 0; j < 4; ++j) { x[j] = x[j] + f[j] * rstd * Cg[j];
;                 if (XOUT_B) { u32x2 w; w.x = pk_bf16(x[j].x, x[j].y); w.y = pk_bf16(x[j].z, x[j].w); *(GAS u32x2*)(xoutb + (size_t)row * DM + 256 * j + 4 * lane) = w;
;                     x[j] = (f32x4){__uint_as_float(w.x << 16), __uint_as_float(w.x & 0xffff0000u), __uint_as_float(w.y << 16), __uint_as_float(w.y & 0xffff0000u)}; }
;                 else __builtin_nontemporal_store(x[j], (GAS f32x4*)(xout + (size_t)row * DM + 256 * j + 4 * lane)); }
;         }
.LBB0_637:
	v_lshl_add_u64 v[86:87], s[10:11], 0, v[16:17]
	s_add_i32 s6, s15, 1
	v_lshlrev_b32_e32 v70, 16, v72
	v_and_b32_e32 v71, 0xffff0000, v72
	v_lshlrev_b32_e32 v72, 16, v73
	v_and_b32_e32 v73, 0xffff0000, v73
	v_lshlrev_b32_e32 v74, 16, v76
	v_and_b32_e32 v75, 0xffff0000, v76
	v_lshlrev_b32_e32 v76, 16, v77
	v_and_b32_e32 v77, 0xffff0000, v77
	v_add_co_u32_e32 v92, vcc, s13, v86
	v_lshlrev_b32_e32 v78, 16, v80
	v_and_b32_e32 v79, 0xffff0000, v80
	v_lshlrev_b32_e32 v80, 16, v81
	v_and_b32_e32 v81, 0xffff0000, v81
	v_lshl_add_u64 v[90:91], s[8:9], 0, v[16:17]
	s_cmp_lt_i32 s15, s70
	v_mul_f32_e32 v94, v71, v71
	v_mul_f32_e32 v95, v73, v73
	v_mul_f32_e32 v96, v75, v75
	v_mul_f32_e32 v97, v77, v77
	v_addc_co_u32_e32 v93, vcc, 0, v87, vcc
	v_lshlrev_b32_e32 v82, 16, v84
	v_and_b32_e32 v83, 0xffff0000, v84
	v_lshlrev_b32_e32 v84, 16, v85
	v_and_b32_e32 v85, 0xffff0000, v85
	v_mul_f32_e32 v98, v79, v79
	v_mul_f32_e32 v99, v81, v81
	v_add_co_u32_e32 v86, vcc, s14, v90
	s_cselect_b64 s[4:5], -1, 0
	v_fmac_f32_e32 v94, v70, v70
	v_fmac_f32_e32 v95, v72, v72
	v_fmac_f32_e32 v96, v74, v74
	v_fmac_f32_e32 v97, v76, v76
	v_mul_f32_e32 v100, v83, v83
	v_mul_f32_e32 v101, v85, v85
	v_addc_co_u32_e32 v87, vcc, 0, v91, vcc
	v_fmac_f32_e32 v98, v78, v78
	v_fmac_f32_e32 v99, v80, v80
	s_and_b64 s[4:5], s[4:5], exec
	v_add_f32_e32 v90, v94, v95
	v_add_f32_e32 v91, v96, v97
	v_fmac_f32_e32 v100, v82, v82
	v_fmac_f32_e32 v101, v84, v84
	v_add_f32_e32 v94, v98, v99
	s_cselect_b32 s16, s6, s15
	v_add_f32_e32 v90, v91, v90
	v_add_f32_e32 v95, v100, v101
	s_ashr_i32 s17, s16, 31
	v_add_f32_e32 v90, v94, v90
	s_mov_b32 s15, s6
	s_lshl_b64 s[6:7], s[16:17], 11
	v_add_f32_e32 v96, v95, v90
	v_lshl_add_u64 v[90:91], v[50:51], 0, s[6:7]
	v_lshl_add_u64 v[94:95], v[52:53], 0, s[6:7]
	v_add_f32_dpp v112, v96, v96 quad_perm:[1,0,3,2] row_mask:0xf bank_mask:0xf bound_ctrl:1
	s_mov_b64 exec, s[4:5]
	global_load_dwordx2 v[96:97], v[90:91], off nt
	global_load_dwordx2 v[98:99], v[90:91], off offset:512 nt
	global_load_dwordx2 v[100:101], v[90:91], off offset:1024 nt
	global_load_dwordx2 v[102:103], v[90:91], off offset:1536 nt
	global_load_dwordx2 v[104:105], v[94:95], off nt
	global_load_dwordx2 v[106:107], v[94:95], off offset:512 nt
	global_load_dwordx2 v[108:109], v[94:95], off offset:1024 nt
	global_load_dwordx2 v[110:111], v[94:95], off offset:1536 nt
	s_mov_b64 exec, -1
	s_nop 4
	v_add_f32_dpp v90, v112, v112 quad_perm:[2,3,0,1] row_mask:0xf bank_mask:0xf bound_ctrl:1
	s_add_u32 s8, s8, 0x800
	s_addc_u32 s9, s9, 0
	v_add_f32_dpp v90, v90, v90 row_half_mirror row_mask:0xf bank_mask:0xf bound_ctrl:1
	s_add_u32 s10, s10, 0x800
	s_addc_u32 s11, s11, 0
	v_add_f32_dpp v90, v90, v90 row_mirror row_mask:0xf bank_mask:0xf bound_ctrl:1
	v_mov_b32_e32 v91, v90
	s_nop 1
	v_permlane16_swap_b32_e32 v90, v91
	v_add_f32_e32 v90, v90, v91
	v_mov_b32_e32 v91, v90
	s_nop 1
	v_permlane32_swap_b32_e32 v90, v91
	v_add_f32_e32 v90, v90, v91
	v_fmamk_f32 v90, v90, 0x3a800000, v88
	v_mul_f32_e32 v91, 0x4f800000, v90
	v_cmp_gt_f32_e32 vcc, s12, v90
	s_nop 1
	v_cndmask_b32_e32 v90, v90, v91, vcc
	v_sqrt_f32_e32 v91, v90
	s_nop 0
	v_add_u32_e32 v94, -1, v91
	v_add_u32_e32 v95, 1, v91
	v_fma_f32 v112, -v94, v91, v90
	v_fma_f32 v113, -v95, v91, v90
	v_cmp_ge_f32_e64 s[6:7], 0, v112
	s_nop 1
	v_cndmask_b32_e64 v91, v91, v94, s[6:7]
	v_cmp_lt_f32_e64 s[6:7], 0, v113
	s_nop 1
	v_cndmask_b32_e64 v91, v91, v95, s[6:7]
	v_mul_f32_e32 v94, 0x37800000, v91
	v_cndmask_b32_e32 v91, v91, v94, vcc
	v_cmp_class_f32_e32 vcc, v90, v89
	s_nop 1
	v_cndmask_b32_e32 v90, v91, v90, vcc
	v_div_scale_f32 v91, s[6:7], v90, v90, 1.0
	v_rcp_f32_e32 v95, v91
	v_div_scale_f32 v94, vcc, 1.0, v90, 1.0
	v_fma_f32 v112, -v91, v95, 1.0
	v_fmac_f32_e32 v95, v112, v95
	v_mul_f32_e32 v112, v94, v95
	v_fma_f32 v113, -v91, v112, v94
	v_fmac_f32_e32 v112, v113, v95
	v_fma_f32 v91, -v91, v112, v94
	v_div_fmas_f32 v91, v91, v95, v112
	v_div_fixup_f32 v90, v91, v90, 1.0
	v_pk_mul_f32 v[70:71], v[70:71], v[90:91] op_sel_hi:[1,0]
	v_pk_mul_f32 v[72:73], v[72:73], v[90:91] op_sel_hi:[1,0]
	v_pk_fma_f32 v[54:55], v[20:21], v[70:71], v[54:55]
	v_pk_mul_f32 v[74:75], v[74:75], v[90:91] op_sel_hi:[1,0]
	v_pk_mul_f32 v[76:77], v[76:77], v[90:91] op_sel_hi:[1,0]
	v_pk_fma_f32 v[56:57], v[18:19], v[72:73], v[56:57]
	v_cvt_pk_bf16_f32 v54, v54, v55
	v_pk_mul_f32 v[78:79], v[78:79], v[90:91] op_sel_hi:[1,0]
	v_cvt_pk_bf16_f32 v55, v56, v57
	v_pk_mul_f32 v[80:81], v[80:81], v[90:91] op_sel_hi:[1,0]
	v_pk_mul_f32 v[82:83], v[82:83], v[90:91] op_sel_hi:[1,0]
	v_pk_fma_f32 v[60:61], v[42:43], v[76:77], v[60:61]
	v_pk_fma_f32 v[58:59], v[44:45], v[74:75], v[58:59]
	global_store_dwordx2 v[92:93], v[54:55], off sc1
	v_lshlrev_b32_e32 v70, 16, v54
	v_and_b32_e32 v71, 0xffff0000, v54
	v_lshlrev_b32_e32 v74, 16, v55
	v_and_b32_e32 v75, 0xffff0000, v55
	v_cvt_pk_bf16_f32 v54, v58, v59
	v_cvt_pk_bf16_f32 v55, v60, v61
	v_pk_mul_f32 v[84:85], v[84:85], v[90:91] op_sel_hi:[1,0]
	v_pk_fma_f32 v[64:65], v[22:23], v[80:81], v[64:65]
	v_pk_fma_f32 v[62:63], v[24:25], v[78:79], v[62:63]
	v_pk_fma_f32 v[66:67], v[48:49], v[82:83], v[66:67]
	global_store_dwordx2 v[92:93], v[54:55], off offset:512 sc1
	v_lshlrev_b32_e32 v78, 16, v54
	v_and_b32_e32 v79, 0xffff0000, v54
	v_lshlrev_b32_e32 v82, 16, v55
	v_and_b32_e32 v83, 0xffff0000, v55
	v_cvt_pk_bf16_f32 v54, v62, v63
	v_cvt_pk_bf16_f32 v55, v64, v65
	v_mul_f32_e32 v56, v71, v71
	v_mul_f32_e32 v57, v75, v75
	v_pk_fma_f32 v[68:69], v[46:47], v[84:85], v[68:69]
	global_store_dwordx2 v[92:93], v[54:55], off offset:1024 sc1
	v_lshlrev_b32_e32 v90, 16, v54
	v_and_b32_e32 v91, 0xffff0000, v54
	v_lshlrev_b32_e32 v94, 16, v55
	v_and_b32_e32 v95, 0xffff0000, v55
	v_cvt_pk_bf16_f32 v54, v66, v67
	v_cvt_pk_bf16_f32 v55, v68, v69
	v_fmac_f32_e32 v56, v70, v70
	v_fmac_f32_e32 v57, v74, v74
	v_mul_f32_e32 v58, v79, v79
	v_mul_f32_e32 v59, v83, v83
	global_store_dwordx2 v[92:93], v[54:55], off offset:1536 sc1
	v_lshlrev_b32_e32 v92, 16, v54
	v_and_b32_e32 v93, 0xffff0000, v54
	v_lshlrev_b32_e32 v112, 16, v55
	v_and_b32_e32 v113, 0xffff0000, v55
	v_add_f32_e32 v54, v56, v57
	v_fmac_f32_e32 v58, v78, v78
	v_fmac_f32_e32 v59, v82, v82
	v_mul_f32_e32 v55, v91, v91
	v_mul_f32_e32 v56, v95, v95
	v_add_f32_e32 v57, v58, v59
	v_fmac_f32_e32 v55, v90, v90
	v_fmac_f32_e32 v56, v94, v94
	v_mul_f32_e32 v58, v93, v93
	v_mul_f32_e32 v59, v113, v113
	v_add_f32_e32 v54, v54, v57
	v_add_f32_e32 v55, v55, v56
	v_fmac_f32_e32 v58, v92, v92
	v_fmac_f32_e32 v59, v112, v112
	v_add_f32_e32 v54, v54, v55
	v_add_f32_e32 v55, v58, v59
	v_add_f32_e32 v54, v54, v55
	s_waitcnt vmcnt(10)
; #define GAS __attribute__((address_space(1)))
; __device__ __forceinline__ float wave_sum(float v) { return xrow_sum(row16_sum(v)); }
; __device__ __forceinline__ unsigned pk_bf16(float lo, float hi) { return pg8::cvt_pk_bf16(lo, hi); }
; __device__ __forceinline__ void xcd_barrier(const XcdBarrier& b) {
;     asm volatile("s_waitcnt vmcnt(0)" ::: "memory");
;     __syncthreads();
;     if (threadIdx.x == 0) {
;         unsigned* bar = b.bar;
;         __builtin_amdgcn_s_waitcnt(0);
;         unsigned nloc = b.st[0], nx = b.st[1];
;         if (nloc == 0u) { xcd_barrier_complete(bar, b.x, nloc, nx); b.st[0] = nloc; b.st[1] = nx; }
; template <bool HAS_F, bool HAS_H, bool XIN_B = false, bool XOUT_B = false> ...
;     ...
;         if (HAS_H) {
;             float ss = 0.f;
; #pragma unroll
;             for (int j = 0; j < 4; ++j) ss += (x[j].x * x[j].x + x[j].y * x[j].y) + (x[j].z * x[j].z + x[j].w * x[j].w);
;             const float rstd = 1.0f / sqrtf(wave_sum(ss) * (1.0f / DM) + RMS_EPS);
; #pragma unroll
;             for (int j = 0; j < 4; ++j) { const f32x4 h = x[j] * rstd * A[j] + Sh[j]; u32x2 w; w.x = pk_bf16(h.x, h.y); w.y = pk_bf16(h.z, h.w);
;                 *(GAS u32x2*)(H + (size_t)row * DM + 256 * j + 4 * lane) = w; }
	v_lshlrev_b32_e32 v61, 16, v98
	v_lshlrev_b32_e32 v63, 16, v99
	v_add_f32_dpp v54, v54, v54 quad_perm:[1,0,3,2] row_mask:0xf bank_mask:0xf bound_ctrl:1
	v_and_b32_e32 v64, 0xffff0000, v99
	s_waitcnt vmcnt(9)
	v_lshlrev_b32_e32 v67, 16, v101
	v_add_f32_dpp v54, v54, v54 quad_perm:[2,3,0,1] row_mask:0xf bank_mask:0xf bound_ctrl:1
	v_and_b32_e32 v60, 0xffff0000, v97
	v_and_b32_e32 v62, 0xffff0000, v98
	v_add_f32_dpp v54, v54, v54 row_half_mirror row_mask:0xf bank_mask:0xf bound_ctrl:1
	v_lshlrev_b32_e32 v65, 16, v100
	v_and_b32_e32 v66, 0xffff0000, v100
	v_add_f32_dpp v54, v54, v54 row_mirror row_mask:0xf bank_mask:0xf bound_ctrl:1
	v_mov_b32_e32 v55, v54
	s_nop 1
	v_permlane16_swap_b32_e32 v54, v55
	v_add_f32_e32 v54, v54, v55
	v_mov_b32_e32 v55, v54
	s_nop 1
	v_permlane32_swap_b32_e32 v54, v55
	v_add_f32_e32 v54, v54, v55
	v_fmamk_f32 v54, v54, 0x3a800000, v88
	v_mul_f32_e32 v55, 0x4f800000, v54
	v_cmp_gt_f32_e32 vcc, s12, v54
	v_and_b32_e32 v68, 0xffff0000, v101
	s_waitcnt vmcnt(8)
	v_lshlrev_b32_e32 v69, 16, v102
	v_cndmask_b32_e32 v54, v54, v55, vcc
	v_sqrt_f32_e32 v55, v54
	v_and_b32_e32 v98, 0xffff0000, v103
	s_waitcnt vmcnt(4)
	v_mov_b64_e32 v[84:85], v[110:111]
	v_mov_b64_e32 v[80:81], v[108:109]
	v_add_u32_e32 v56, -1, v55
	v_add_u32_e32 v57, 1, v55
	v_fma_f32 v58, -v56, v55, v54
	v_fma_f32 v59, -v57, v55, v54
	v_cmp_ge_f32_e64 s[6:7], 0, v58
	v_and_b32_e32 v58, 0xffff0000, v96
	v_mov_b64_e32 v[76:77], v[106:107]
	v_cndmask_b32_e64 v55, v55, v56, s[6:7]
	v_cmp_lt_f32_e64 s[6:7], 0, v59
	v_lshlrev_b32_e32 v59, 16, v97
	v_lshlrev_b32_e32 v97, 16, v103
	v_cndmask_b32_e64 v55, v55, v57, s[6:7]
	v_mul_f32_e32 v56, 0x37800000, v55
	v_cndmask_b32_e32 v55, v55, v56, vcc
	v_cmp_class_f32_e32 vcc, v54, v89
	v_lshlrev_b32_e32 v57, 16, v96
	v_and_b32_e32 v96, 0xffff0000, v102
	v_cndmask_b32_e32 v114, v55, v54, vcc
	v_div_scale_f32 v54, s[6:7], v114, v114, 1.0
	v_rcp_f32_e32 v115, v54
	v_div_scale_f32 v55, vcc, 1.0, v114, 1.0
	v_mov_b64_e32 v[72:73], v[104:105]
	v_fma_f32 v56, -v54, v115, 1.0
	v_fmac_f32_e32 v115, v56, v115
	v_mul_f32_e32 v116, v55, v115
	v_fma_f32 v56, -v54, v116, v55
	v_fmac_f32_e32 v116, v56, v115
	v_fma_f32 v99, -v54, v116, v55
	v_mov_b32_e32 v55, v58
	v_mov_b32_e32 v58, v61
	v_mov_b32_e32 v61, v64
	v_mov_b32_e32 v64, v67
	v_mov_b32_e32 v67, v96
	v_div_fmas_f32 v96, v99, v115, v116
	v_div_fixup_f32 v96, v96, v114, 1.0
	v_pk_mul_f32 v[70:71], v[70:71], v[96:97] op_sel_hi:[1,0]
	v_pk_mul_f32 v[74:75], v[74:75], v[96:97] op_sel_hi:[1,0]
	v_pk_fma_f32 v[70:71], v[28:29], v[70:71], v[0:1]
	v_pk_mul_f32 v[78:79], v[78:79], v[96:97] op_sel_hi:[1,0]
	v_pk_mul_f32 v[82:83], v[82:83], v[96:97] op_sel_hi:[1,0]
	v_pk_fma_f32 v[74:75], v[26:27], v[74:75], v[2:3]
	v_cvt_pk_bf16_f32 v70, v70, v71
	v_pk_mul_f32 v[90:91], v[90:91], v[96:97] op_sel_hi:[1,0]
	v_cvt_pk_bf16_f32 v71, v74, v75
	v_pk_mul_f32 v[94:95], v[94:95], v[96:97] op_sel_hi:[1,0]
	v_pk_fma_f32 v[82:83], v[30:31], v[82:83], v[10:11]
	v_pk_fma_f32 v[78:79], v[32:33], v[78:79], v[8:9]
	global_store_dwordx2 v[86:87], v[70:71], off sc1
	v_cvt_pk_bf16_f32 v70, v78, v79
	v_cvt_pk_bf16_f32 v71, v82, v83
	v_mov_b32_e32 v54, v57
	v_mov_b32_e32 v56, v59
	v_mov_b32_e32 v57, v60
	v_mov_b32_e32 v59, v62
	v_mov_b32_e32 v60, v63
	v_mov_b32_e32 v62, v65
	v_mov_b32_e32 v63, v66
	v_mov_b32_e32 v65, v68
	v_mov_b32_e32 v66, v69
	v_mov_b32_e32 v68, v97
	v_mov_b32_e32 v69, v98
	v_pk_mul_f32 v[92:93], v[92:93], v[96:97] op_sel_hi:[1,0]
	v_pk_mul_f32 v[96:97], v[112:113], v[96:97] op_sel_hi:[1,0]
	v_pk_fma_f32 v[94:95], v[34:35], v[94:95], v[6:7]
	v_pk_fma_f32 v[90:91], v[36:37], v[90:91], v[4:5]
	global_store_dwordx2 v[86:87], v[70:71], off offset:512 sc1
	v_cvt_pk_bf16_f32 v70, v90, v91
	v_cvt_pk_bf16_f32 v71, v94, v95
	s_mov_b64 vcc, s[4:5]
	v_pk_fma_f32 v[96:97], v[38:39], v[96:97], v[14:15]
	v_pk_fma_f32 v[92:93], v[40:41], v[92:93], v[12:13]
	global_store_dwordx2 v[86:87], v[70:71], off offset:1024 sc1
	v_cvt_pk_bf16_f32 v70, v92, v93
	v_cvt_pk_bf16_f32 v71, v96, v97
	global_store_dwordx2 v[86:87], v[70:71], off offset:1536 sc1
	s_cbranch_vccnz .LBB0_637
	s_waitcnt vmcnt(0)
	s_barrier
	s_and_saveexec_b64 s[4:5], s[26:27]
	s_xor_b64 s[52:53], exec, s[4:5]
	s_cbranch_execz .LBB0_683
	s_add_i32 s3, 0, 0x20020
	v_mov_b32_e32 v0, s3
	s_waitcnt vmcnt(0) expcnt(0) lgkmcnt(0)
	ds_read_b32 v2, v0
	s_add_i32 s3, 0, 0x20024
	v_mov_b32_e32 v0, s3
	ds_read_b32 v0, v0
	s_waitcnt lgkmcnt(1)
	v_cmp_ne_u32_e32 vcc, 0, v2
	s_cbranch_vccnz .LBB0_653
	s_add_u32 s4, s40, 0x80200
	s_addc_u32 s5, s41, 0
	s_add_u32 s8, s40, 0x80400
	s_addc_u32 s9, s41, 0
	s_add_u32 s10, s40, 0x80500
	s_addc_u32 s11, s41, 0
	s_add_u32 s12, s40, 0x80600
	s_addc_u32 s13, s41, 0
	s_add_u32 s14, s40, 0x80700
	s_addc_u32 s15, s41, 0
	s_add_u32 s16, s40, 0x80800
	s_addc_u32 s17, s41, 0
	s_add_u32 s18, s40, 0x80900
	s_addc_u32 s19, s41, 0
	s_add_u32 s20, s40, 0x80a00
	s_addc_u32 s21, s41, 0
	s_add_u32 s22, s40, 0x80b00
	s_addc_u32 s23, s41, 0
	s_add_u32 s28, s40, 0x80c00
	s_addc_u32 s29, s41, 0
	s_add_u32 s30, s40, 0x80d00
	s_addc_u32 s31, s41, 0
	s_add_u32 s34, s40, 0x80e00
	s_addc_u32 s35, s41, 0
	s_add_u32 s36, s40, 0x80f00
	s_addc_u32 s37, s41, 0
	s_add_u32 s48, s40, 0x81000
	s_addc_u32 s49, s41, 0
	s_add_u32 s54, s40, 0x81100
	s_addc_u32 s55, s41, 0
	s_add_u32 s56, s40, 0x81200
	s_addc_u32 s57, s41, 0
	s_add_u32 s58, s40, 0x81300
	s_mul_i32 s24, s43, s92
	s_addc_u32 s59, s41, 0
	s_mul_i32 s24, s24, s42
	s_mov_b32 s25, 1
	s_mov_b64 s[6:7], 0
	s_waitcnt lgkmcnt(0)
	v_mov_b64_e32 v[0:1], s[8:9]
	v_mov_b64_e32 v[2:3], s[10:11]
	v_mov_b64_e32 v[4:5], s[12:13]
	v_mov_b64_e32 v[6:7], s[14:15]
	v_mov_b64_e32 v[8:9], s[16:17]
	v_mov_b64_e32 v[10:11], s[18:19]
	v_mov_b64_e32 v[12:13], s[20:21]
	v_mov_b64_e32 v[14:15], s[22:23]
	v_mov_b64_e32 v[16:17], s[28:29]
	v_mov_b64_e32 v[18:19], s[30:31]
	v_mov_b64_e32 v[20:21], s[34:35]
	v_mov_b64_e32 v[22:23], s[36:37]
	v_mov_b64_e32 v[24:25], s[48:49]
	v_mov_b64_e32 v[26:27], s[54:55]
	v_mov_b64_e32 v[28:29], s[56:57]
	v_mov_b64_e32 v[30:31], s[58:59]
	s_branch .LBB0_643
